# GLA kdec k tile staged by LDS-DMA (global_load_lds), its wait moved behind the gate maths
# speedup vs baseline: 1.0040x; 1.0008x over previous
; #define LAS __attribute__((address_space(3)))
; #define GAS __attribute__((address_space(1)))
; __device__ __forceinline__ void phase_gla_kdec(Frame& F) {
;     ...
;             for (int ks = 0; ks < 4; ++ks) { const int k0 = 128 * w + 32 * ks + 8 * g; const bf16x8 bfr = *(const GAS bf16x8*)(WGT + li * D + k0);
; #pragma unroll
;                 for (int mb = 0; mb < 4; ++mb) { const bf16x8 afr = *(const GAS bf16x8*)(H2 + (m0 + 16 * mb + li) * D + k0); ga[mb] = __builtin_amdgcn_mfma_f32_16x16x32_bf16(afr, bfr, ga[mb], 0, 0, 0); } }
; #pragma unroll
;             for (int mb = 0; mb < 4; ++mb)
; #pragma unroll
;                 for (int i = 0; i < 4; ++i) gpart[(w * 64 + 16 * mb + 4 * g + i) * 16 + li] = ga[mb][i];
;         }
; #pragma unroll
;         for (int i = 0; i < 8; ++i) { const int idx = F.tid + NTHR * i, row = idx >> 6, ch = idx & 63;
;             *(LAS u32x4*)(kt + row * KP + ch * 8) = *(const GAS u32x4*)(QKVR + (m0 + row) * NQKVR + QKW + ch * 8); }
;         u32x4 rv[4];
; #pragma unroll
;         for (int i = 0; i < 4; ++i) { const int idx = F.tid + NTHR * i, row = idx >> 5, ch = idx & 31; rv[i] = *(const GAS u32x4*)(QKVR + (m0 + row) * NQKVR + 2 * QKW + ch * 8); }
.LBB0_817:
	s_ashr_i32 s15, s14, 31
	s_lshl_b64 s[16:17], s[14:15], 6
	s_waitcnt vmcnt(11)
	v_mov_b32_e32 v1, s17
	v_or_b32_e32 v0, s16, v30
	s_waitcnt vmcnt(9)
	v_mov_b32_e32 v9, s17
	v_or_b32_e32 v8, s16, v40
	s_waitcnt vmcnt(8)
	v_mov_b32_e32 v13, s17
	v_or_b32_e32 v12, s16, v42
	v_mov_b32_e32 v89, s17
	v_or_b32_e32 v88, s16, v44
	v_lshlrev_b64 v[154:155], 11, v[0:1]
	v_lshlrev_b64 v[162:163], 11, v[8:9]
	v_lshlrev_b64 v[166:167], 11, v[12:13]
	v_lshlrev_b64 v[168:169], 11, v[88:89]
	v_lshl_add_u64 v[4:5], v[38:39], 0, v[154:155]
	v_lshl_add_u64 v[8:9], v[38:39], 0, v[162:163]
	v_lshl_add_u64 v[12:13], v[38:39], 0, v[166:167]
	v_lshl_add_u64 v[88:89], v[38:39], 0, v[168:169]
	s_barrier
	global_load_dwordx4 v[0:3], v[36:37], off
	v_lshl_add_u64 v[92:93], v[46:47], 0, v[154:155]
	global_load_dwordx4 v[4:7], v[4:5], off
	v_lshl_add_u64 v[122:123], v[46:47], 0, v[162:163]
	global_load_dwordx4 v[8:11], v[8:9], off
	v_lshl_add_u64 v[126:127], v[46:47], 0, v[166:167]
	global_load_dwordx4 v[12:15], v[12:13], off
	v_lshl_add_u64 v[130:131], v[46:47], 0, v[168:169]
	global_load_dwordx4 v[88:91], v[88:89], off
	s_nop 0
	global_load_dwordx4 v[92:95], v[92:93], off
	s_nop 0
	global_load_dwordx4 v[118:121], v[36:37], off offset:64
	v_lshl_add_u64 v[134:135], v[48:49], 0, v[154:155]
	global_load_dwordx4 v[122:125], v[122:123], off
	v_lshl_add_u64 v[142:143], v[48:49], 0, v[162:163]
	global_load_dwordx4 v[126:129], v[126:127], off
	v_lshl_add_u64 v[146:147], v[48:49], 0, v[166:167]
	global_load_dwordx4 v[130:133], v[130:131], off
	s_nop 0
	global_load_dwordx4 v[134:137], v[134:135], off
	s_nop 0
	global_load_dwordx4 v[138:141], v[36:37], off offset:128
	v_lshl_add_u64 v[150:151], v[48:49], 0, v[168:169]
	global_load_dwordx4 v[142:145], v[142:143], off
	v_lshl_add_u64 v[154:155], v[50:51], 0, v[154:155]
	global_load_dwordx4 v[146:149], v[146:147], off
	v_lshl_add_u64 v[166:167], v[50:51], 0, v[166:167]
	global_load_dwordx4 v[150:153], v[150:151], off
	s_nop 0
	global_load_dwordx4 v[154:157], v[154:155], off
	s_nop 0
	global_load_dwordx4 v[158:161], v[36:37], off offset:192
	v_lshl_add_u64 v[162:163], v[50:51], 0, v[162:163]
	global_load_dwordx4 v[162:165], v[162:163], off
	v_lshl_add_u64 v[170:171], s[16:17], 0, v[54:55]
	v_lshl_add_u64 v[172:173], s[16:17], 0, v[56:57]
	v_lshl_add_u64 v[174:175], s[16:17], 0, v[58:59]
	v_lshl_add_u64 v[176:177], s[16:17], 0, v[64:65]
	s_waitcnt vmcnt(16)
	v_mfma_f32_16x16x32_bf16 v[4:7], v[4:7], v[0:3], 0
	s_waitcnt vmcnt(15)
	v_mfma_f32_16x16x32_bf16 v[8:11], v[8:11], v[0:3], 0
	s_waitcnt vmcnt(14)
	v_mfma_f32_16x16x32_bf16 v[12:15], v[12:15], v[0:3], 0
	s_waitcnt vmcnt(13)
	v_mfma_f32_16x16x32_bf16 v[0:3], v[88:91], v[0:3], 0
	global_load_dwordx4 v[88:91], v[166:167], off
	v_lshl_add_u64 v[166:167], s[16:17], 0, v[52:53]
	s_waitcnt vmcnt(10)
	v_mfma_f32_16x16x32_bf16 v[12:15], v[126:129], v[118:121], v[12:15]
	v_mad_u64_u32 v[126:127], s[0:1], v166, s21, v[76:77]
	v_mad_u64_u32 v[128:129], s[0:1], v170, s21, v[76:77]
	v_mfma_f32_16x16x32_bf16 v[4:7], v[92:95], v[118:121], v[4:7]
	v_lshl_add_u64 v[92:93], v[50:51], 0, v[168:169]
	global_load_dwordx4 v[92:95], v[92:93], off
	v_mad_i32_i24 v127, v167, s21, v127
	s_waitcnt vmcnt(6)
	v_mfma_f32_16x16x32_bf16 v[12:15], v[146:149], v[138:141], v[12:15]
	v_mad_i32_i24 v129, v171, s21, v129
	v_mfma_f32_16x16x32_bf16 v[8:11], v[122:125], v[118:121], v[8:11]
	v_lshl_add_u64 v[122:123], s[16:17], 0, v[60:61]
	v_lshl_add_u64 v[124:125], s[16:17], 0, v[62:63]
	v_mad_u64_u32 v[178:179], s[0:1], v124, s21, v[76:77]
	v_mfma_f32_16x16x32_bf16 v[0:3], v[130:133], v[118:121], v[0:3]
	v_mad_u64_u32 v[130:131], s[0:1], v172, s21, v[76:77]
	v_mad_u64_u32 v[132:133], s[0:1], v174, s21, v[76:77]
	v_mfma_f32_16x16x32_bf16 v[4:7], v[134:137], v[138:141], v[4:7]
	v_mad_u64_u32 v[134:135], s[0:1], v122, s21, v[76:77]
	v_mad_i32_i24 v131, v173, s21, v131
	v_mfma_f32_16x16x32_bf16 v[8:11], v[142:145], v[138:141], v[8:11]
	v_mad_u64_u32 v[142:143], s[0:1], v176, s21, v[76:77]
	v_mad_i32_i24 v133, v175, s21, v133
	v_mad_i32_i24 v135, v123, s21, v135
	v_mad_i32_i24 v143, v177, s21, v143
	s_waitcnt vmcnt(5)
	v_mfma_f32_16x16x32_bf16 v[0:3], v[150:153], v[138:141], v[0:3]
	v_mad_i32_i24 v179, v125, s21, v179
	v_readfirstlane_b32 s4, v101
	s_nop 0
	s_add_i32 m0, s4, 0xc00
	s_nop 0
	global_load_lds_dwordx4 v[126:127], off offset:1024
	v_readfirstlane_b32 s4, v102
	s_nop 0
	s_add_i32 m0, s4, 0xc00
	s_nop 0
	global_load_lds_dwordx4 v[128:129], off offset:1024
	s_nop 0
	v_readfirstlane_b32 s4, v103
	s_nop 0
	s_add_i32 m0, s4, 0xc00
	s_nop 0
	global_load_lds_dwordx4 v[130:131], off offset:1024
	s_nop 0
	v_readfirstlane_b32 s4, v104
	s_nop 0
	s_add_i32 m0, s4, 0xc00
	s_nop 0
	global_load_lds_dwordx4 v[132:133], off offset:1024
	s_nop 0
	v_readfirstlane_b32 s4, v105
	s_nop 0
	s_add_i32 m0, s4, 0xc00
	s_nop 0
	global_load_lds_dwordx4 v[134:135], off offset:1024
	s_nop 0
	v_readfirstlane_b32 s4, v106
	s_nop 0
	s_add_i32 m0, s4, 0xc00
	s_nop 0
	global_load_lds_dwordx4 v[178:179], off offset:1024
	s_waitcnt vmcnt(9)
	v_mfma_f32_16x16x32_bf16 v[4:7], v[154:157], v[158:161], v[4:7]
	s_waitcnt vmcnt(8)
	v_mfma_f32_16x16x32_bf16 v[8:11], v[162:165], v[158:161], v[8:11]
	s_waitcnt vmcnt(7)
	v_mfma_f32_16x16x32_bf16 v[12:15], v[88:91], v[158:161], v[12:15]
	v_lshl_add_u64 v[88:89], s[16:17], 0, v[66:67]
	v_mad_u64_u32 v[144:145], s[0:1], v88, s21, v[76:77]
	v_mad_i32_i24 v145, v89, s21, v145
	v_readfirstlane_b32 s4, v107
	s_nop 0
	s_add_i32 m0, s4, 0xc00
	s_nop 0
	global_load_lds_dwordx4 v[142:143], off offset:1024
	s_nop 0
	v_readfirstlane_b32 s4, v108
	s_nop 0
	s_add_i32 m0, s4, 0xc00
	s_nop 0
	global_load_lds_dwordx4 v[144:145], off offset:1024
	s_waitcnt vmcnt(8)
	v_mfma_f32_16x16x32_bf16 v[0:3], v[92:95], v[158:161], v[0:3]
	ds_write2_b32 v116, v4, v5 offset1:16
	ds_write2_b32 v116, v6, v7 offset0:32 offset1:48
	v_add_u32_e32 v4, 0x400, v116
	ds_write2_b32 v4, v8, v9 offset1:16
	ds_write2_b32 v4, v10, v11 offset0:32 offset1:48
	v_add_u32_e32 v4, 0x800, v116
	ds_write2_b32 v4, v12, v13 offset1:16
	ds_write2_b32 v4, v14, v15 offset0:32 offset1:48
	v_add_u32_e32 v4, 0xc00, v116
	v_lshl_add_u64 v[8:9], s[16:17], 0, v[72:73]
	ds_write2_b32 v4, v0, v1 offset1:16
	ds_write2_b32 v4, v2, v3 offset0:32 offset1:48
	v_lshl_add_u64 v[0:1], s[16:17], 0, v[68:69]
	v_mad_u64_u32 v[2:3], s[0:1], v0, s21, v[78:79]
	v_mad_u64_u32 v[88:89], s[0:1], v8, s21, v[78:79]
	v_mad_i32_i24 v3, v1, s21, v3
	v_lshl_add_u64 v[0:1], s[16:17], 0, v[70:71]
	v_mad_i32_i24 v89, v9, s21, v89
	v_lshl_add_u64 v[8:9], s[16:17], 0, v[74:75]
	v_mad_u64_u32 v[4:5], s[0:1], v0, s21, v[78:79]
	v_mad_u64_u32 v[90:91], s[0:1], v8, s21, v[78:79]
	v_mad_i32_i24 v5, v1, s21, v5
	v_mad_i32_i24 v91, v9, s21, v91
	global_load_dwordx4 v[0:3], v[2:3], off offset:2048
	s_nop 0
	global_load_dwordx4 v[4:7], v[4:5], off offset:2048
	s_nop 0
	global_load_dwordx4 v[8:11], v[88:89], off offset:2048
	global_load_dwordx4 v[12:15], v[90:91], off offset:2048
	s_waitcnt lgkmcnt(0)
	s_barrier
; #define LAS __attribute__((address_space(3)))
; __device__ __forceinline__ void phase_gla_kdec(Frame& F) {
;     ...
;         { const int sIdx = F.tid >> 3, r2 = (F.tid & 7) * 2; float s0 = 0.f, s1 = 0.f;
; #pragma unroll
;             for (int v = 0; v < 8; ++v) { s0 += gpart[(v * 64 + sIdx) * 16 + r2]; s1 += gpart[(v * 64 + sIdx) * 16 + r2 + 1]; }
;             glr[sIdx * 16 + r2] = s0; glr[sIdx * 16 + r2 + 1] = s1; }
;         __syncthreads();
;         { float gc[CH]; float run = 0.f;
; #pragma unroll
;             for (int s = 0; s < CH; ++s) { float a = bgc;
; #pragma unroll
;                 for (int r4 = 0; r4 < 4; ++r4) { const f32x4 gv = *(const LAS f32x4*)(glr + s * 16 + r4 * 4); a += (gv.x * w2c[4 * r4] + gv.y * w2c[4 * r4 + 1]) + (gv.z * w2c[4 * r4 + 2] + gv.w * w2c[4 * r4 + 3]); }
;                 run += fast_logsigmoid(a) * (1.f / 16.f); gc[s] = run; }
	ds_read2st64_b64 v[88:91], v109 offset1:8
	ds_read2st64_b64 v[92:95], v109 offset0:16 offset1:24
	ds_read2st64_b64 v[118:121], v109 offset0:32 offset1:40
	s_lshl_b64 s[0:1], s[14:15], 11
	s_mov_b32 s16, s19
	s_waitcnt lgkmcnt(2)
	v_pk_add_f32 v[88:89], v[88:89], 0 op_sel_hi:[1,0]
	s_nop 0
	v_pk_add_f32 v[122:123], v[88:89], v[90:91]
	ds_read2st64_b64 v[88:91], v109 offset0:48 offset1:56
	s_waitcnt lgkmcnt(2)
	v_pk_add_f32 v[92:93], v[122:123], v[92:93]
	s_nop 0
	v_pk_add_f32 v[92:93], v[92:93], v[94:95]
	s_waitcnt lgkmcnt(1)
	v_pk_add_f32 v[92:93], v[92:93], v[118:119]
	s_nop 0
	v_pk_add_f32 v[92:93], v[92:93], v[120:121]
	s_waitcnt lgkmcnt(0)
	v_pk_add_f32 v[88:89], v[92:93], v[88:89]
	s_nop 0
	v_pk_add_f32 v[88:89], v[88:89], v[90:91]
	ds_write_b64 v110, v[88:89]
	s_waitcnt lgkmcnt(0)
	s_barrier
	v_mbcnt_lo_u32_b32 v117, -1, 0
	v_mbcnt_hi_u32_b32 v117, -1, v117
	v_and_b32_e32 v118, 15, v117
	v_lshrrev_b32_e32 v119, 4, v117
	v_lshrrev_b32_e32 v184, 2, v118
	v_and_b32_e32 v186, 3, v118
	v_lshlrev_b32_e32 v184, 10, v184
	v_lshl_or_b32 v184, v186, 6, v184
	v_lshl_or_b32 v184, v119, 4, v184
	ds_read_b128 v[232:235], v184 offset:0
	ds_read_b128 v[236:239], v184 offset:256
	ds_read_b128 v[240:243], v184 offset:512
	ds_read_b128 v[244:247], v184 offset:768
	v_mov_b32_e32 v188, s90
	v_and_b32_e32 v188, 0xffffffc0, v188
	v_lshlrev_b32_e32 v185, 1, v188
	v_lshl_add_u32 v185, v118, 3, v185
	v_mul_u32_u24_e32 v186, 0x4100, v119
	v_add_u32_e32 v185, v185, v186
	v_add_u32_e32 v185, 0x1000, v185
	v_add_u32_e32 v187, v188, v118
	v_lshlrev_b32_e32 v187, 4, v187
	v_add_u32_e32 v187, 0x19800, v187
	v_add_u32_e32 v186, v188, v117
	v_lshlrev_b32_e32 v186, 4, v186
	v_add_u32_e32 v186, 0x19800, v186
	s_waitcnt lgkmcnt(0)
	v_mfma_f32_16x16x4_f32 v[120:123], v232, v16, 0
	v_mfma_f32_16x16x4_f32 v[124:127], v232, v17, 0
	v_mfma_f32_16x16x4_f32 v[128:131], v232, v18, 0
	v_mfma_f32_16x16x4_f32 v[132:135], v232, v19, 0
	v_mfma_f32_16x16x4_f32 v[120:123], v233, v20, v[120:123]
	v_mfma_f32_16x16x4_f32 v[124:127], v233, v21, v[124:127]
	v_mfma_f32_16x16x4_f32 v[128:131], v233, v22, v[128:131]
	v_mfma_f32_16x16x4_f32 v[132:135], v233, v23, v[132:135]
	v_mfma_f32_16x16x4_f32 v[120:123], v234, v24, v[120:123]
	v_mfma_f32_16x16x4_f32 v[124:127], v234, v25, v[124:127]
	v_mfma_f32_16x16x4_f32 v[128:131], v234, v26, v[128:131]
	v_mfma_f32_16x16x4_f32 v[132:135], v234, v27, v[132:135]
	v_mfma_f32_16x16x4_f32 v[120:123], v235, v224, v[120:123]
	v_mfma_f32_16x16x4_f32 v[124:127], v235, v225, v[124:127]
	v_mfma_f32_16x16x4_f32 v[128:131], v235, v226, v[128:131]
	v_mfma_f32_16x16x4_f32 v[132:135], v235, v227, v[132:135]
	v_mfma_f32_16x16x4_f32 v[136:139], v236, v16, 0
	v_mfma_f32_16x16x4_f32 v[140:143], v236, v17, 0
	v_mfma_f32_16x16x4_f32 v[144:147], v236, v18, 0
	v_mfma_f32_16x16x4_f32 v[148:151], v236, v19, 0
	v_mfma_f32_16x16x4_f32 v[136:139], v237, v20, v[136:139]
	v_mfma_f32_16x16x4_f32 v[140:143], v237, v21, v[140:143]
	v_mfma_f32_16x16x4_f32 v[144:147], v237, v22, v[144:147]
	v_mfma_f32_16x16x4_f32 v[148:151], v237, v23, v[148:151]
	v_mfma_f32_16x16x4_f32 v[136:139], v238, v24, v[136:139]
	v_mfma_f32_16x16x4_f32 v[140:143], v238, v25, v[140:143]
	v_mfma_f32_16x16x4_f32 v[144:147], v238, v26, v[144:147]
	v_mfma_f32_16x16x4_f32 v[148:151], v238, v27, v[148:151]
	v_mfma_f32_16x16x4_f32 v[136:139], v239, v224, v[136:139]
	v_mfma_f32_16x16x4_f32 v[140:143], v239, v225, v[140:143]
	v_mfma_f32_16x16x4_f32 v[144:147], v239, v226, v[144:147]
	v_mfma_f32_16x16x4_f32 v[148:151], v239, v227, v[148:151]
	v_mfma_f32_16x16x4_f32 v[152:155], v240, v16, 0
	v_mfma_f32_16x16x4_f32 v[156:159], v240, v17, 0
	v_mfma_f32_16x16x4_f32 v[160:163], v240, v18, 0
	v_mfma_f32_16x16x4_f32 v[164:167], v240, v19, 0
	v_mfma_f32_16x16x4_f32 v[152:155], v241, v20, v[152:155]
	v_mfma_f32_16x16x4_f32 v[156:159], v241, v21, v[156:159]
	v_mfma_f32_16x16x4_f32 v[160:163], v241, v22, v[160:163]
	v_mfma_f32_16x16x4_f32 v[164:167], v241, v23, v[164:167]
	v_mfma_f32_16x16x4_f32 v[152:155], v242, v24, v[152:155]
	v_mfma_f32_16x16x4_f32 v[156:159], v242, v25, v[156:159]
	v_mfma_f32_16x16x4_f32 v[160:163], v242, v26, v[160:163]
	v_mfma_f32_16x16x4_f32 v[164:167], v242, v27, v[164:167]
	v_mfma_f32_16x16x4_f32 v[152:155], v243, v224, v[152:155]
	v_mfma_f32_16x16x4_f32 v[156:159], v243, v225, v[156:159]
	v_mfma_f32_16x16x4_f32 v[160:163], v243, v226, v[160:163]
	v_mfma_f32_16x16x4_f32 v[164:167], v243, v227, v[164:167]
	v_mfma_f32_16x16x4_f32 v[168:171], v244, v16, 0
	v_mfma_f32_16x16x4_f32 v[172:175], v244, v17, 0
	v_mfma_f32_16x16x4_f32 v[176:179], v244, v18, 0
	v_mfma_f32_16x16x4_f32 v[180:183], v244, v19, 0
	v_mfma_f32_16x16x4_f32 v[168:171], v245, v20, v[168:171]
	v_mfma_f32_16x16x4_f32 v[172:175], v245, v21, v[172:175]
	v_mfma_f32_16x16x4_f32 v[176:179], v245, v22, v[176:179]
	v_mfma_f32_16x16x4_f32 v[180:183], v245, v23, v[180:183]
	v_mfma_f32_16x16x4_f32 v[168:171], v246, v24, v[168:171]
	v_mfma_f32_16x16x4_f32 v[172:175], v246, v25, v[172:175]
	v_mfma_f32_16x16x4_f32 v[176:179], v246, v26, v[176:179]
	v_mfma_f32_16x16x4_f32 v[180:183], v246, v27, v[180:183]
	v_mfma_f32_16x16x4_f32 v[168:171], v247, v224, v[168:171]
	v_mfma_f32_16x16x4_f32 v[172:175], v247, v225, v[172:175]
	v_mfma_f32_16x16x4_f32 v[176:179], v247, v226, v[176:179]
	v_mfma_f32_16x16x4_f32 v[180:183], v247, v227, v[180:183]
	s_nop 15
	v_add_f32_e32 v120, v228, v120
	v_add_f32_e32 v121, v228, v121
	v_add_f32_e32 v122, v228, v122
	v_add_f32_e32 v123, v228, v123
	v_mul_f32_e64 v232, |v120|, s22
	v_mul_f32_e64 v233, |v121|, s22
	v_mul_f32_e64 v234, |v122|, s22
	v_mul_f32_e64 v235, |v123|, s22
	v_exp_f32_e32 v232, v232
	v_exp_f32_e32 v233, v233
; #define LAS __attribute__((address_space(3)))
; __device__ __forceinline__ float fast_logsigmoid(float a) {
;     const float e = __builtin_amdgcn_exp2f(-1.4426950408889634f * __builtin_fabsf(a));
;     return fminf(a, 0.f) - 0.6931471805599453f * __builtin_amdgcn_logf(1.f + e);
; }
; __device__ __forceinline__ void phase_gla_kdec(Frame& F) {
;     ...
;             for (int s = 0; s < CH; ++s) { float a = bgc;
; #pragma unroll
;                 for (int r4 = 0; r4 < 4; ++r4) { const f32x4 gv = *(const LAS f32x4*)(glr + s * 16 + r4 * 4); a += (gv.x * w2c[4 * r4] + gv.y * w2c[4 * r4 + 1]) + (gv.z * w2c[4 * r4 + 2] + gv.w * w2c[4 * r4 + 3]); }
;                 run += fast_logsigmoid(a) * (1.f / 16.f); gc[s] = run; }
	v_exp_f32_e32 v234, v234
	v_exp_f32_e32 v235, v235
	v_add_f32_e32 v232, 1.0, v232
	v_add_f32_e32 v233, 1.0, v233
	v_add_f32_e32 v234, 1.0, v234
	v_add_f32_e32 v235, 1.0, v235
	v_log_f32_e32 v232, v232
	v_log_f32_e32 v233, v233
	v_log_f32_e32 v234, v234
	v_log_f32_e32 v235, v235
	v_min_f32_e32 v120, 0, v120
	v_min_f32_e32 v121, 0, v121
	v_min_f32_e32 v122, 0, v122
	v_min_f32_e32 v123, 0, v123
	v_fmac_f32_e32 v120, 0xbf317218, v232
	v_fmac_f32_e32 v121, 0xbf317218, v233
	v_fmac_f32_e32 v122, 0xbf317218, v234
	v_fmac_f32_e32 v123, 0xbf317218, v235
	v_mul_f32_e32 v120, s23, v120
	v_mul_f32_e32 v121, s23, v121
	v_mul_f32_e32 v122, s23, v122
	v_mul_f32_e32 v123, s23, v123
	v_add_f32_e32 v124, v229, v124
	v_add_f32_e32 v125, v229, v125
	v_add_f32_e32 v126, v229, v126
	v_add_f32_e32 v127, v229, v127
	v_mul_f32_e64 v232, |v124|, s22
	v_mul_f32_e64 v233, |v125|, s22
	v_mul_f32_e64 v234, |v126|, s22
	v_mul_f32_e64 v235, |v127|, s22
	v_exp_f32_e32 v232, v232
	v_exp_f32_e32 v233, v233
	v_exp_f32_e32 v234, v234
	v_exp_f32_e32 v235, v235
	v_add_f32_e32 v232, 1.0, v232
	v_add_f32_e32 v233, 1.0, v233
	v_add_f32_e32 v234, 1.0, v234
	v_add_f32_e32 v235, 1.0, v235
	v_log_f32_e32 v232, v232
	v_log_f32_e32 v233, v233
	v_log_f32_e32 v234, v234
	v_log_f32_e32 v235, v235
	v_min_f32_e32 v124, 0, v124
	v_min_f32_e32 v125, 0, v125
	v_min_f32_e32 v126, 0, v126
	v_min_f32_e32 v127, 0, v127
	v_fmac_f32_e32 v124, 0xbf317218, v232
	v_fmac_f32_e32 v125, 0xbf317218, v233
	v_fmac_f32_e32 v126, 0xbf317218, v234
	v_fmac_f32_e32 v127, 0xbf317218, v235
	v_mul_f32_e32 v124, s23, v124
	v_mul_f32_e32 v125, s23, v125
	v_mul_f32_e32 v126, s23, v126
	v_mul_f32_e32 v127, s23, v127
	v_add_f32_e32 v128, v230, v128
	v_add_f32_e32 v129, v230, v129
	v_add_f32_e32 v130, v230, v130
	v_add_f32_e32 v131, v230, v131
	v_mul_f32_e64 v232, |v128|, s22
	v_mul_f32_e64 v233, |v129|, s22
	v_mul_f32_e64 v234, |v130|, s22
	v_mul_f32_e64 v235, |v131|, s22
	v_exp_f32_e32 v232, v232
	v_exp_f32_e32 v233, v233
	v_exp_f32_e32 v234, v234
	v_exp_f32_e32 v235, v235
	v_add_f32_e32 v232, 1.0, v232
	v_add_f32_e32 v233, 1.0, v233
	v_add_f32_e32 v234, 1.0, v234
	v_add_f32_e32 v235, 1.0, v235
	v_log_f32_e32 v232, v232
	v_log_f32_e32 v233, v233
	v_log_f32_e32 v234, v234
	v_log_f32_e32 v235, v235
	v_min_f32_e32 v128, 0, v128
	v_min_f32_e32 v129, 0, v129
	v_min_f32_e32 v130, 0, v130
	v_min_f32_e32 v131, 0, v131
	v_fmac_f32_e32 v128, 0xbf317218, v232
	v_fmac_f32_e32 v129, 0xbf317218, v233
	v_fmac_f32_e32 v130, 0xbf317218, v234
	v_fmac_f32_e32 v131, 0xbf317218, v235
	v_mul_f32_e32 v128, s23, v128
	v_mul_f32_e32 v129, s23, v129
	v_mul_f32_e32 v130, s23, v130
	v_mul_f32_e32 v131, s23, v131
	v_add_f32_e32 v132, v231, v132
	v_add_f32_e32 v133, v231, v133
	v_add_f32_e32 v134, v231, v134
	v_add_f32_e32 v135, v231, v135
	v_mul_f32_e64 v232, |v132|, s22
	v_mul_f32_e64 v233, |v133|, s22
	v_mul_f32_e64 v234, |v134|, s22
	v_mul_f32_e64 v235, |v135|, s22
	v_exp_f32_e32 v232, v232
	v_exp_f32_e32 v233, v233
	v_exp_f32_e32 v234, v234
	v_exp_f32_e32 v235, v235
	v_add_f32_e32 v232, 1.0, v232
	v_add_f32_e32 v233, 1.0, v233
	v_add_f32_e32 v234, 1.0, v234
	v_add_f32_e32 v235, 1.0, v235
	v_log_f32_e32 v232, v232
	v_log_f32_e32 v233, v233
	v_log_f32_e32 v234, v234
	v_log_f32_e32 v235, v235
	v_min_f32_e32 v132, 0, v132
	v_min_f32_e32 v133, 0, v133
	v_min_f32_e32 v134, 0, v134
	v_min_f32_e32 v135, 0, v135
	v_fmac_f32_e32 v132, 0xbf317218, v232
	v_fmac_f32_e32 v133, 0xbf317218, v233
	v_fmac_f32_e32 v134, 0xbf317218, v234
	v_fmac_f32_e32 v135, 0xbf317218, v235
	v_mul_f32_e32 v132, s23, v132
	v_mul_f32_e32 v133, s23, v133
	v_mul_f32_e32 v134, s23, v134
	v_mul_f32_e32 v135, s23, v135
	v_add_f32_e32 v136, v228, v136
	v_add_f32_e32 v137, v228, v137
	v_add_f32_e32 v138, v228, v138
	v_add_f32_e32 v139, v228, v139
	v_mul_f32_e64 v232, |v136|, s22
	v_mul_f32_e64 v233, |v137|, s22
	v_mul_f32_e64 v234, |v138|, s22
	v_mul_f32_e64 v235, |v139|, s22
	v_exp_f32_e32 v232, v232
	v_exp_f32_e32 v233, v233
	v_exp_f32_e32 v234, v234
	v_exp_f32_e32 v235, v235
	v_add_f32_e32 v232, 1.0, v232
	v_add_f32_e32 v233, 1.0, v233
	v_add_f32_e32 v234, 1.0, v234
	v_add_f32_e32 v235, 1.0, v235
	v_log_f32_e32 v232, v232
	v_log_f32_e32 v233, v233
	v_log_f32_e32 v234, v234
	v_log_f32_e32 v235, v235
	v_min_f32_e32 v136, 0, v136
	v_min_f32_e32 v137, 0, v137
	v_min_f32_e32 v138, 0, v138
	v_min_f32_e32 v139, 0, v139
	v_fmac_f32_e32 v136, 0xbf317218, v232
	v_fmac_f32_e32 v137, 0xbf317218, v233
	v_fmac_f32_e32 v138, 0xbf317218, v234
	v_fmac_f32_e32 v139, 0xbf317218, v235
	v_mul_f32_e32 v136, s23, v136
	v_mul_f32_e32 v137, s23, v137
	v_mul_f32_e32 v138, s23, v138
	v_mul_f32_e32 v139, s23, v139
	v_add_f32_e32 v140, v229, v140
	v_add_f32_e32 v141, v229, v141
	v_add_f32_e32 v142, v229, v142
	v_add_f32_e32 v143, v229, v143
	v_mul_f32_e64 v232, |v140|, s22
	v_mul_f32_e64 v233, |v141|, s22
	v_mul_f32_e64 v234, |v142|, s22
	v_mul_f32_e64 v235, |v143|, s22
	v_exp_f32_e32 v232, v232
	v_exp_f32_e32 v233, v233
	v_exp_f32_e32 v234, v234
	v_exp_f32_e32 v235, v235
	v_add_f32_e32 v232, 1.0, v232
	v_add_f32_e32 v233, 1.0, v233
	v_add_f32_e32 v234, 1.0, v234
	v_add_f32_e32 v235, 1.0, v235
	v_log_f32_e32 v232, v232
	v_log_f32_e32 v233, v233
	v_log_f32_e32 v234, v234
	v_log_f32_e32 v235, v235
	v_min_f32_e32 v140, 0, v140
	v_min_f32_e32 v141, 0, v141
	v_min_f32_e32 v142, 0, v142
	v_min_f32_e32 v143, 0, v143
	v_fmac_f32_e32 v140, 0xbf317218, v232
	v_fmac_f32_e32 v141, 0xbf317218, v233
	v_fmac_f32_e32 v142, 0xbf317218, v234
	v_fmac_f32_e32 v143, 0xbf317218, v235
	v_mul_f32_e32 v140, s23, v140
	v_mul_f32_e32 v141, s23, v141
	v_mul_f32_e32 v142, s23, v142
	v_mul_f32_e32 v143, s23, v143
	v_add_f32_e32 v144, v230, v144
; #define LAS __attribute__((address_space(3)))
; __device__ __forceinline__ float fast_logsigmoid(float a) {
;     const float e = __builtin_amdgcn_exp2f(-1.4426950408889634f * __builtin_fabsf(a));
;     return fminf(a, 0.f) - 0.6931471805599453f * __builtin_amdgcn_logf(1.f + e);
; }
; __device__ __forceinline__ void phase_gla_kdec(Frame& F) {
;     ...
;             for (int s = 0; s < CH; ++s) { float a = bgc;
; #pragma unroll
;                 for (int r4 = 0; r4 < 4; ++r4) { const f32x4 gv = *(const LAS f32x4*)(glr + s * 16 + r4 * 4); a += (gv.x * w2c[4 * r4] + gv.y * w2c[4 * r4 + 1]) + (gv.z * w2c[4 * r4 + 2] + gv.w * w2c[4 * r4 + 3]); }
;                 run += fast_logsigmoid(a) * (1.f / 16.f); gc[s] = run; }
	v_add_f32_e32 v145, v230, v145
	v_add_f32_e32 v146, v230, v146
	v_add_f32_e32 v147, v230, v147
	v_mul_f32_e64 v232, |v144|, s22
	v_mul_f32_e64 v233, |v145|, s22
	v_mul_f32_e64 v234, |v146|, s22
	v_mul_f32_e64 v235, |v147|, s22
	v_exp_f32_e32 v232, v232
	v_exp_f32_e32 v233, v233
	v_exp_f32_e32 v234, v234
	v_exp_f32_e32 v235, v235
	v_add_f32_e32 v232, 1.0, v232
	v_add_f32_e32 v233, 1.0, v233
	v_add_f32_e32 v234, 1.0, v234
	v_add_f32_e32 v235, 1.0, v235
	v_log_f32_e32 v232, v232
	v_log_f32_e32 v233, v233
	v_log_f32_e32 v234, v234
	v_log_f32_e32 v235, v235
	v_min_f32_e32 v144, 0, v144
	v_min_f32_e32 v145, 0, v145
	v_min_f32_e32 v146, 0, v146
	v_min_f32_e32 v147, 0, v147
	v_fmac_f32_e32 v144, 0xbf317218, v232
	v_fmac_f32_e32 v145, 0xbf317218, v233
	v_fmac_f32_e32 v146, 0xbf317218, v234
	v_fmac_f32_e32 v147, 0xbf317218, v235
	v_mul_f32_e32 v144, s23, v144
	v_mul_f32_e32 v145, s23, v145
	v_mul_f32_e32 v146, s23, v146
	v_mul_f32_e32 v147, s23, v147
	v_add_f32_e32 v148, v231, v148
	v_add_f32_e32 v149, v231, v149
	v_add_f32_e32 v150, v231, v150
	v_add_f32_e32 v151, v231, v151
	v_mul_f32_e64 v232, |v148|, s22
	v_mul_f32_e64 v233, |v149|, s22
	v_mul_f32_e64 v234, |v150|, s22
	v_mul_f32_e64 v235, |v151|, s22
	v_exp_f32_e32 v232, v232
	v_exp_f32_e32 v233, v233
	v_exp_f32_e32 v234, v234
	v_exp_f32_e32 v235, v235
	v_add_f32_e32 v232, 1.0, v232
	v_add_f32_e32 v233, 1.0, v233
	v_add_f32_e32 v234, 1.0, v234
	v_add_f32_e32 v235, 1.0, v235
	v_log_f32_e32 v232, v232
	v_log_f32_e32 v233, v233
	v_log_f32_e32 v234, v234
	v_log_f32_e32 v235, v235
	v_min_f32_e32 v148, 0, v148
	v_min_f32_e32 v149, 0, v149
	v_min_f32_e32 v150, 0, v150
	v_min_f32_e32 v151, 0, v151
	v_fmac_f32_e32 v148, 0xbf317218, v232
	v_fmac_f32_e32 v149, 0xbf317218, v233
	v_fmac_f32_e32 v150, 0xbf317218, v234
	v_fmac_f32_e32 v151, 0xbf317218, v235
	v_mul_f32_e32 v148, s23, v148
	v_mul_f32_e32 v149, s23, v149
	v_mul_f32_e32 v150, s23, v150
	v_mul_f32_e32 v151, s23, v151
	v_add_f32_e32 v152, v228, v152
	v_add_f32_e32 v153, v228, v153
	v_add_f32_e32 v154, v228, v154
	v_add_f32_e32 v155, v228, v155
	v_mul_f32_e64 v232, |v152|, s22
	v_mul_f32_e64 v233, |v153|, s22
	v_mul_f32_e64 v234, |v154|, s22
	v_mul_f32_e64 v235, |v155|, s22
	v_exp_f32_e32 v232, v232
	v_exp_f32_e32 v233, v233
	v_exp_f32_e32 v234, v234
	v_exp_f32_e32 v235, v235
	v_add_f32_e32 v232, 1.0, v232
	v_add_f32_e32 v233, 1.0, v233
	v_add_f32_e32 v234, 1.0, v234
	v_add_f32_e32 v235, 1.0, v235
	v_log_f32_e32 v232, v232
	v_log_f32_e32 v233, v233
	v_log_f32_e32 v234, v234
	v_log_f32_e32 v235, v235
	v_min_f32_e32 v152, 0, v152
	v_min_f32_e32 v153, 0, v153
	v_min_f32_e32 v154, 0, v154
	v_min_f32_e32 v155, 0, v155
	v_fmac_f32_e32 v152, 0xbf317218, v232
	v_fmac_f32_e32 v153, 0xbf317218, v233
	v_fmac_f32_e32 v154, 0xbf317218, v234
	v_fmac_f32_e32 v155, 0xbf317218, v235
	v_mul_f32_e32 v152, s23, v152
	v_mul_f32_e32 v153, s23, v153
	v_mul_f32_e32 v154, s23, v154
	v_mul_f32_e32 v155, s23, v155
	v_add_f32_e32 v156, v229, v156
	v_add_f32_e32 v157, v229, v157
	v_add_f32_e32 v158, v229, v158
	v_add_f32_e32 v159, v229, v159
	v_mul_f32_e64 v232, |v156|, s22
	v_mul_f32_e64 v233, |v157|, s22
	v_mul_f32_e64 v234, |v158|, s22
	v_mul_f32_e64 v235, |v159|, s22
	v_exp_f32_e32 v232, v232
	v_exp_f32_e32 v233, v233
	v_exp_f32_e32 v234, v234
	v_exp_f32_e32 v235, v235
	v_add_f32_e32 v232, 1.0, v232
	v_add_f32_e32 v233, 1.0, v233
	v_add_f32_e32 v234, 1.0, v234
	v_add_f32_e32 v235, 1.0, v235
	v_log_f32_e32 v232, v232
	v_log_f32_e32 v233, v233
	v_log_f32_e32 v234, v234
	v_log_f32_e32 v235, v235
	v_min_f32_e32 v156, 0, v156
	v_min_f32_e32 v157, 0, v157
	v_min_f32_e32 v158, 0, v158
	v_min_f32_e32 v159, 0, v159
	v_fmac_f32_e32 v156, 0xbf317218, v232
	v_fmac_f32_e32 v157, 0xbf317218, v233
	v_fmac_f32_e32 v158, 0xbf317218, v234
	v_fmac_f32_e32 v159, 0xbf317218, v235
	v_mul_f32_e32 v156, s23, v156
	v_mul_f32_e32 v157, s23, v157
	v_mul_f32_e32 v158, s23, v158
	v_mul_f32_e32 v159, s23, v159
	v_add_f32_e32 v160, v230, v160
	v_add_f32_e32 v161, v230, v161
	v_add_f32_e32 v162, v230, v162
	v_add_f32_e32 v163, v230, v163
	v_mul_f32_e64 v232, |v160|, s22
	v_mul_f32_e64 v233, |v161|, s22
	v_mul_f32_e64 v234, |v162|, s22
	v_mul_f32_e64 v235, |v163|, s22
	v_exp_f32_e32 v232, v232
	v_exp_f32_e32 v233, v233
	v_exp_f32_e32 v234, v234
	v_exp_f32_e32 v235, v235
	v_add_f32_e32 v232, 1.0, v232
	v_add_f32_e32 v233, 1.0, v233
	v_add_f32_e32 v234, 1.0, v234
	v_add_f32_e32 v235, 1.0, v235
	v_log_f32_e32 v232, v232
	v_log_f32_e32 v233, v233
	v_log_f32_e32 v234, v234
	v_log_f32_e32 v235, v235
	v_min_f32_e32 v160, 0, v160
	v_min_f32_e32 v161, 0, v161
	v_min_f32_e32 v162, 0, v162
	v_min_f32_e32 v163, 0, v163
	v_fmac_f32_e32 v160, 0xbf317218, v232
	v_fmac_f32_e32 v161, 0xbf317218, v233
	v_fmac_f32_e32 v162, 0xbf317218, v234
	v_fmac_f32_e32 v163, 0xbf317218, v235
	v_mul_f32_e32 v160, s23, v160
	v_mul_f32_e32 v161, s23, v161
	v_mul_f32_e32 v162, s23, v162
	v_mul_f32_e32 v163, s23, v163
	v_add_f32_e32 v164, v231, v164
	v_add_f32_e32 v165, v231, v165
	v_add_f32_e32 v166, v231, v166
	v_add_f32_e32 v167, v231, v167
	v_mul_f32_e64 v232, |v164|, s22
	v_mul_f32_e64 v233, |v165|, s22
	v_mul_f32_e64 v234, |v166|, s22
	v_mul_f32_e64 v235, |v167|, s22
	v_exp_f32_e32 v232, v232
	v_exp_f32_e32 v233, v233
	v_exp_f32_e32 v234, v234
	v_exp_f32_e32 v235, v235
	v_add_f32_e32 v232, 1.0, v232
	v_add_f32_e32 v233, 1.0, v233
	v_add_f32_e32 v234, 1.0, v234
	v_add_f32_e32 v235, 1.0, v235
	v_log_f32_e32 v232, v232
	v_log_f32_e32 v233, v233
	v_log_f32_e32 v234, v234
	v_log_f32_e32 v235, v235
	v_min_f32_e32 v164, 0, v164
	v_min_f32_e32 v165, 0, v165
	v_min_f32_e32 v166, 0, v166
	v_min_f32_e32 v167, 0, v167
	v_fmac_f32_e32 v164, 0xbf317218, v232
; #define LAS __attribute__((address_space(3)))
; __device__ __forceinline__ void phase_gla_kdec(Frame& F) {
;     ...
;             for (int s = 0; s < CH; ++s) { float a = bgc;
; #pragma unroll
;                 for (int r4 = 0; r4 < 4; ++r4) { const f32x4 gv = *(const LAS f32x4*)(glr + s * 16 + r4 * 4); a += (gv.x * w2c[4 * r4] + gv.y * w2c[4 * r4 + 1]) + (gv.z * w2c[4 * r4 + 2] + gv.w * w2c[4 * r4 + 3]); }
;                 run += fast_logsigmoid(a) * (1.f / 16.f); gc[s] = run; }
	v_fmac_f32_e32 v165, 0xbf317218, v233
	v_fmac_f32_e32 v166, 0xbf317218, v234
	v_fmac_f32_e32 v167, 0xbf317218, v235
	v_mul_f32_e32 v164, s23, v164
	v_mul_f32_e32 v165, s23, v165
	v_mul_f32_e32 v166, s23, v166
	v_mul_f32_e32 v167, s23, v167
	v_add_f32_e32 v168, v228, v168
	v_add_f32_e32 v169, v228, v169
	v_add_f32_e32 v170, v228, v170
	v_add_f32_e32 v171, v228, v171
	v_mul_f32_e64 v232, |v168|, s22
	v_mul_f32_e64 v233, |v169|, s22
	v_mul_f32_e64 v234, |v170|, s22
	v_mul_f32_e64 v235, |v171|, s22
	v_exp_f32_e32 v232, v232
	v_exp_f32_e32 v233, v233
	v_exp_f32_e32 v234, v234
	v_exp_f32_e32 v235, v235
	v_add_f32_e32 v232, 1.0, v232
	v_add_f32_e32 v233, 1.0, v233
	v_add_f32_e32 v234, 1.0, v234
	v_add_f32_e32 v235, 1.0, v235
	v_log_f32_e32 v232, v232
	v_log_f32_e32 v233, v233
	v_log_f32_e32 v234, v234
	v_log_f32_e32 v235, v235
	v_min_f32_e32 v168, 0, v168
	v_min_f32_e32 v169, 0, v169
	v_min_f32_e32 v170, 0, v170
	v_min_f32_e32 v171, 0, v171
	v_fmac_f32_e32 v168, 0xbf317218, v232
	v_fmac_f32_e32 v169, 0xbf317218, v233
	v_fmac_f32_e32 v170, 0xbf317218, v234
	v_fmac_f32_e32 v171, 0xbf317218, v235
	v_mul_f32_e32 v168, s23, v168
	v_mul_f32_e32 v169, s23, v169
	v_mul_f32_e32 v170, s23, v170
	v_mul_f32_e32 v171, s23, v171
	v_add_f32_e32 v172, v229, v172
	v_add_f32_e32 v173, v229, v173
	v_add_f32_e32 v174, v229, v174
	v_add_f32_e32 v175, v229, v175
	v_mul_f32_e64 v232, |v172|, s22
	v_mul_f32_e64 v233, |v173|, s22
	v_mul_f32_e64 v234, |v174|, s22
	v_mul_f32_e64 v235, |v175|, s22
	v_exp_f32_e32 v232, v232
	v_exp_f32_e32 v233, v233
	v_exp_f32_e32 v234, v234
	v_exp_f32_e32 v235, v235
	v_add_f32_e32 v232, 1.0, v232
	v_add_f32_e32 v233, 1.0, v233
	v_add_f32_e32 v234, 1.0, v234
	v_add_f32_e32 v235, 1.0, v235
	v_log_f32_e32 v232, v232
	v_log_f32_e32 v233, v233
	v_log_f32_e32 v234, v234
	v_log_f32_e32 v235, v235
	v_min_f32_e32 v172, 0, v172
	v_min_f32_e32 v173, 0, v173
	v_min_f32_e32 v174, 0, v174
	v_min_f32_e32 v175, 0, v175
	v_fmac_f32_e32 v172, 0xbf317218, v232
	v_fmac_f32_e32 v173, 0xbf317218, v233
	v_fmac_f32_e32 v174, 0xbf317218, v234
	v_fmac_f32_e32 v175, 0xbf317218, v235
	v_mul_f32_e32 v172, s23, v172
	v_mul_f32_e32 v173, s23, v173
	v_mul_f32_e32 v174, s23, v174
	v_mul_f32_e32 v175, s23, v175
	v_add_f32_e32 v176, v230, v176
	v_add_f32_e32 v177, v230, v177
	v_add_f32_e32 v178, v230, v178
	v_add_f32_e32 v179, v230, v179
	v_mul_f32_e64 v232, |v176|, s22
	v_mul_f32_e64 v233, |v177|, s22
	v_mul_f32_e64 v234, |v178|, s22
	v_mul_f32_e64 v235, |v179|, s22
	v_exp_f32_e32 v232, v232
	v_exp_f32_e32 v233, v233
	v_exp_f32_e32 v234, v234
	v_exp_f32_e32 v235, v235
	v_add_f32_e32 v232, 1.0, v232
	v_add_f32_e32 v233, 1.0, v233
	v_add_f32_e32 v234, 1.0, v234
	v_add_f32_e32 v235, 1.0, v235
	v_log_f32_e32 v232, v232
	v_log_f32_e32 v233, v233
	v_log_f32_e32 v234, v234
	v_log_f32_e32 v235, v235
	v_min_f32_e32 v176, 0, v176
	v_min_f32_e32 v177, 0, v177
	v_min_f32_e32 v178, 0, v178
	v_min_f32_e32 v179, 0, v179
	v_fmac_f32_e32 v176, 0xbf317218, v232
	v_fmac_f32_e32 v177, 0xbf317218, v233
	v_fmac_f32_e32 v178, 0xbf317218, v234
	v_fmac_f32_e32 v179, 0xbf317218, v235
	v_mul_f32_e32 v176, s23, v176
	v_mul_f32_e32 v177, s23, v177
	v_mul_f32_e32 v178, s23, v178
	v_mul_f32_e32 v179, s23, v179
	v_add_f32_e32 v180, v231, v180
	v_add_f32_e32 v181, v231, v181
	v_add_f32_e32 v182, v231, v182
	v_add_f32_e32 v183, v231, v183
	v_mul_f32_e64 v232, |v180|, s22
	v_mul_f32_e64 v233, |v181|, s22
	v_mul_f32_e64 v234, |v182|, s22
	v_mul_f32_e64 v235, |v183|, s22
	v_exp_f32_e32 v232, v232
	v_exp_f32_e32 v233, v233
	v_exp_f32_e32 v234, v234
	v_exp_f32_e32 v235, v235
	v_add_f32_e32 v232, 1.0, v232
	v_add_f32_e32 v233, 1.0, v233
	v_add_f32_e32 v234, 1.0, v234
	v_add_f32_e32 v235, 1.0, v235
	v_log_f32_e32 v232, v232
	v_log_f32_e32 v233, v233
	v_log_f32_e32 v234, v234
	v_log_f32_e32 v235, v235
	v_min_f32_e32 v180, 0, v180
	v_min_f32_e32 v181, 0, v181
	v_min_f32_e32 v182, 0, v182
	v_min_f32_e32 v183, 0, v183
	v_fmac_f32_e32 v180, 0xbf317218, v232
	v_fmac_f32_e32 v181, 0xbf317218, v233
	v_fmac_f32_e32 v182, 0xbf317218, v234
	v_fmac_f32_e32 v183, 0xbf317218, v235
	v_mul_f32_e32 v180, s23, v180
	v_mul_f32_e32 v181, s23, v181
	v_mul_f32_e32 v182, s23, v182
	v_mul_f32_e32 v183, s23, v183
	v_add_f32_e32 v121, v120, v121
	v_add_f32_e32 v122, v121, v122
	v_add_f32_e32 v123, v122, v123
	v_add_f32_e32 v136, v123, v136
	v_add_f32_e32 v137, v136, v137
	v_add_f32_e32 v138, v137, v138
	v_add_f32_e32 v139, v138, v139
	v_add_f32_e32 v152, v139, v152
	v_add_f32_e32 v153, v152, v153
	v_add_f32_e32 v154, v153, v154
	v_add_f32_e32 v155, v154, v155
	v_add_f32_e32 v168, v155, v168
	v_add_f32_e32 v169, v168, v169
	v_add_f32_e32 v170, v169, v170
	v_add_f32_e32 v171, v170, v171
	v_add_f32_e32 v125, v124, v125
	v_add_f32_e32 v126, v125, v126
	v_add_f32_e32 v127, v126, v127
	v_add_f32_e32 v140, v127, v140
	v_add_f32_e32 v141, v140, v141
	v_add_f32_e32 v142, v141, v142
	v_add_f32_e32 v143, v142, v143
	v_add_f32_e32 v156, v143, v156
	v_add_f32_e32 v157, v156, v157
	v_add_f32_e32 v158, v157, v158
	v_add_f32_e32 v159, v158, v159
	v_add_f32_e32 v172, v159, v172
	v_add_f32_e32 v173, v172, v173
	v_add_f32_e32 v174, v173, v174
	v_add_f32_e32 v175, v174, v175
	v_add_f32_e32 v129, v128, v129
	v_add_f32_e32 v130, v129, v130
	v_add_f32_e32 v131, v130, v131
	v_add_f32_e32 v144, v131, v144
	v_add_f32_e32 v145, v144, v145
	v_add_f32_e32 v146, v145, v146
	v_add_f32_e32 v147, v146, v147
	v_add_f32_e32 v160, v147, v160
	v_add_f32_e32 v161, v160, v161
	v_add_f32_e32 v162, v161, v162
	v_add_f32_e32 v163, v162, v163
	v_add_f32_e32 v176, v163, v176
	v_add_f32_e32 v177, v176, v177
	v_add_f32_e32 v178, v177, v178
	v_add_f32_e32 v179, v178, v179
	v_add_f32_e32 v133, v132, v133
	v_add_f32_e32 v134, v133, v134
	v_add_f32_e32 v135, v134, v135
	v_add_f32_e32 v148, v135, v148
	v_add_f32_e32 v149, v148, v149
	v_add_f32_e32 v150, v149, v150
	v_add_f32_e32 v151, v150, v151
	v_add_f32_e32 v164, v151, v164
	v_add_f32_e32 v165, v164, v165
	v_add_f32_e32 v166, v165, v166
	v_add_f32_e32 v167, v166, v167
	v_add_f32_e32 v180, v167, v180
	v_add_f32_e32 v181, v180, v181
	v_add_f32_e32 v182, v181, v182
	v_add_f32_e32 v183, v182, v183
	v_mov_b32_e32 v88, v171
	v_mov_b32_e32 v89, v175
	v_mov_b32_e32 v90, v179
	v_mov_b32_e32 v91, v183
	ds_write_b128 v186, v[88:91]
	s_waitcnt lgkmcnt(0)
; __device__ __forceinline__ unsigned f2bf(float f) { unsigned u = __builtin_bit_cast(unsigned, f); return (u + 0x7fffu + ((u >> 16) & 1u)) >> 16; }
; __device__ __forceinline__ void phase_gla_kdec(Frame& F) {
;     ...
;                 run += fast_logsigmoid(a) * (1.f / 16.f); gc[s] = run; }
; #pragma unroll
;             for (int s = 0; s < CH; ++s) { const float kv = bf2f(kt[s * KP + j]);
;                 kt[s * KP + j] = (bf16_t)f2bf(kv * __builtin_amdgcn_exp2f(1.4426950408889634f * (run - gc[s]))); }
;             DEC[(size_t)unit * QKW + j] = __builtin_amdgcn_exp2f(1.4426950408889634f * run); }
	ds_read_b128 v[232:235], v187 offset:0
	ds_read_b128 v[236:239], v187 offset:256
	ds_read_b128 v[240:243], v187 offset:512
	ds_read_b128 v[244:247], v187 offset:768
	v_cmp_eq_u32_e32 vcc, 0, v119
	s_nop 1
	v_cndmask_b32_e64 v92, 0, 1.0, vcc
	v_cmp_gt_u32_e32 vcc, 2, v119
	s_nop 1
	v_cndmask_b32_e64 v93, 0, 1.0, vcc
	v_cmp_gt_u32_e32 vcc, 3, v119
	s_nop 1
	v_cndmask_b32_e64 v94, 0, 1.0, vcc
	s_waitcnt lgkmcnt(0)
	v_mov_b32_e32 v248, v244
	v_fmac_f32_e32 v248, v94, v240
	v_fmac_f32_e32 v248, v93, v236
	v_fmac_f32_e32 v248, v92, v232
	v_mov_b32_e32 v249, v245
	v_fmac_f32_e32 v249, v94, v241
	v_fmac_f32_e32 v249, v93, v237
	v_fmac_f32_e32 v249, v92, v233
	v_mov_b32_e32 v250, v246
	v_fmac_f32_e32 v250, v94, v242
	v_fmac_f32_e32 v250, v93, v238
	v_fmac_f32_e32 v250, v92, v234
	v_mov_b32_e32 v251, v247
	v_fmac_f32_e32 v251, v94, v243
	v_fmac_f32_e32 v251, v93, v239
	v_fmac_f32_e32 v251, v92, v235
	v_mul_f32_e32 v88, 0x3fb8aa3b, v248
	v_mul_f32_e32 v89, 0x3fb8aa3b, v249
	v_mul_f32_e32 v90, 0x3fb8aa3b, v250
	v_mul_f32_e32 v91, 0x3fb8aa3b, v251
	v_exp_f32_e32 v88, v88
	v_exp_f32_e32 v89, v89
	v_exp_f32_e32 v90, v90
	v_exp_f32_e32 v91, v91
	v_mul_u32_u24_e32 v232, 12, v118
	v_mov_b32_e32 v233, 0
	v_lshl_add_u64 v[232:233], v[28:29], 0, v[232:233]
	v_lshl_add_u64 v[232:233], v[232:233], 0, s[0:1]
	s_waitcnt vmcnt(4)
	s_barrier
	v_cmp_eq_u32_e32 vcc, 0, v119
	s_and_b64 exec, exec, vcc
	global_store_dwordx4 v[232:233], v[88:91], off
	s_nop 1
	s_mov_b64 exec, -1
	ds_read_b64 v[232:233], v185 offset:0
	ds_read_b64 v[234:235], v185 offset:1040
	ds_read_b64 v[236:237], v185 offset:2080
	ds_read_b64 v[238:239], v185 offset:3120
	ds_read_b64 v[240:241], v185 offset:4160
	ds_read_b64 v[242:243], v185 offset:5200
	ds_read_b64 v[244:245], v185 offset:6240
	ds_read_b64 v[246:247], v185 offset:7280
	v_sub_f32_e32 v120, v248, v120
	v_mul_f32_e32 v120, 0x3fb8aa3b, v120
	v_exp_f32_e32 v120, v120
	v_sub_f32_e32 v124, v249, v124
	v_mul_f32_e32 v124, 0x3fb8aa3b, v124
	v_exp_f32_e32 v124, v124
	v_sub_f32_e32 v128, v250, v128
	v_mul_f32_e32 v128, 0x3fb8aa3b, v128
	v_exp_f32_e32 v128, v128
	v_sub_f32_e32 v132, v251, v132
	v_mul_f32_e32 v132, 0x3fb8aa3b, v132
	v_exp_f32_e32 v132, v132
	s_waitcnt lgkmcnt(7)
	v_lshlrev_b32_e32 v92, 16, v232
	v_and_b32_e32 v93, 0xffff0000, v232
	v_lshlrev_b32_e32 v94, 16, v233
	v_and_b32_e32 v95, 0xffff0000, v233
	v_mul_f32_e32 v92, v120, v92
	v_mul_f32_e32 v93, v124, v93
	v_mul_f32_e32 v94, v128, v94
	v_mul_f32_e32 v95, v132, v95
	v_cvt_pk_bf16_f32 v88, v92, v93
	v_cvt_pk_bf16_f32 v89, v94, v95
	ds_write_b64 v185, v[88:89] offset:0
	v_sub_f32_e32 v121, v248, v121
	v_mul_f32_e32 v121, 0x3fb8aa3b, v121
	v_exp_f32_e32 v121, v121
	v_sub_f32_e32 v125, v249, v125
	v_mul_f32_e32 v125, 0x3fb8aa3b, v125
	v_exp_f32_e32 v125, v125
	v_sub_f32_e32 v129, v250, v129
	v_mul_f32_e32 v129, 0x3fb8aa3b, v129
	v_exp_f32_e32 v129, v129
	v_sub_f32_e32 v133, v251, v133
	v_mul_f32_e32 v133, 0x3fb8aa3b, v133
	v_exp_f32_e32 v133, v133
	s_waitcnt lgkmcnt(6)
	v_lshlrev_b32_e32 v92, 16, v234
	v_and_b32_e32 v93, 0xffff0000, v234
	v_lshlrev_b32_e32 v94, 16, v235
	v_and_b32_e32 v95, 0xffff0000, v235
	v_mul_f32_e32 v92, v121, v92
	v_mul_f32_e32 v93, v125, v93
	v_mul_f32_e32 v94, v129, v94
	v_mul_f32_e32 v95, v133, v95
	v_cvt_pk_bf16_f32 v90, v92, v93
	v_cvt_pk_bf16_f32 v91, v94, v95
	ds_write_b64 v185, v[90:91] offset:1040
	v_sub_f32_e32 v122, v248, v122
	v_mul_f32_e32 v122, 0x3fb8aa3b, v122
	v_exp_f32_e32 v122, v122
	v_sub_f32_e32 v126, v249, v126
	v_mul_f32_e32 v126, 0x3fb8aa3b, v126
	v_exp_f32_e32 v126, v126
	v_sub_f32_e32 v130, v250, v130
	v_mul_f32_e32 v130, 0x3fb8aa3b, v130
	v_exp_f32_e32 v130, v130
	v_sub_f32_e32 v134, v251, v134
	v_mul_f32_e32 v134, 0x3fb8aa3b, v134
	v_exp_f32_e32 v134, v134
	s_waitcnt lgkmcnt(5)
	v_lshlrev_b32_e32 v92, 16, v236
	v_and_b32_e32 v93, 0xffff0000, v236
	v_lshlrev_b32_e32 v94, 16, v237
	v_and_b32_e32 v95, 0xffff0000, v237
	v_mul_f32_e32 v92, v122, v92
	v_mul_f32_e32 v93, v126, v93
	v_mul_f32_e32 v94, v130, v94
	v_mul_f32_e32 v95, v134, v95
	v_cvt_pk_bf16_f32 v88, v92, v93
	v_cvt_pk_bf16_f32 v89, v94, v95
	ds_write_b64 v185, v[88:89] offset:2080
	v_sub_f32_e32 v123, v248, v123
	v_mul_f32_e32 v123, 0x3fb8aa3b, v123
	v_exp_f32_e32 v123, v123
	v_sub_f32_e32 v127, v249, v127
	v_mul_f32_e32 v127, 0x3fb8aa3b, v127
	v_exp_f32_e32 v127, v127
	v_sub_f32_e32 v131, v250, v131
	v_mul_f32_e32 v131, 0x3fb8aa3b, v131
	v_exp_f32_e32 v131, v131
	v_sub_f32_e32 v135, v251, v135
	v_mul_f32_e32 v135, 0x3fb8aa3b, v135
	v_exp_f32_e32 v135, v135
	s_waitcnt lgkmcnt(4)
	v_lshlrev_b32_e32 v92, 16, v238
	v_and_b32_e32 v93, 0xffff0000, v238
	v_lshlrev_b32_e32 v94, 16, v239
	v_and_b32_e32 v95, 0xffff0000, v239
	v_mul_f32_e32 v92, v123, v92
	v_mul_f32_e32 v93, v127, v93
	v_mul_f32_e32 v94, v131, v94
	v_mul_f32_e32 v95, v135, v95
	v_cvt_pk_bf16_f32 v90, v92, v93
	v_cvt_pk_bf16_f32 v91, v94, v95
	ds_write_b64 v185, v[90:91] offset:3120
	v_sub_f32_e32 v136, v248, v136
	v_mul_f32_e32 v136, 0x3fb8aa3b, v136
	v_exp_f32_e32 v136, v136
	v_sub_f32_e32 v140, v249, v140
	v_mul_f32_e32 v140, 0x3fb8aa3b, v140
	v_exp_f32_e32 v140, v140
	v_sub_f32_e32 v144, v250, v144
	v_mul_f32_e32 v144, 0x3fb8aa3b, v144
	v_exp_f32_e32 v144, v144
	v_sub_f32_e32 v148, v251, v148
	v_mul_f32_e32 v148, 0x3fb8aa3b, v148
	v_exp_f32_e32 v148, v148
	s_waitcnt lgkmcnt(3)
; __device__ __forceinline__ unsigned f2bf(float f) { unsigned u = __builtin_bit_cast(unsigned, f); return (u + 0x7fffu + ((u >> 16) & 1u)) >> 16; }
; __device__ __forceinline__ void phase_gla_kdec(Frame& F) {
;     ...
;             for (int s = 0; s < CH; ++s) { const float kv = bf2f(kt[s * KP + j]);
;                 kt[s * KP + j] = (bf16_t)f2bf(kv * __builtin_amdgcn_exp2f(1.4426950408889634f * (run - gc[s]))); }
	v_lshlrev_b32_e32 v92, 16, v240
	v_and_b32_e32 v93, 0xffff0000, v240
	v_lshlrev_b32_e32 v94, 16, v241
	v_and_b32_e32 v95, 0xffff0000, v241
	v_mul_f32_e32 v92, v136, v92
	v_mul_f32_e32 v93, v140, v93
	v_mul_f32_e32 v94, v144, v94
	v_mul_f32_e32 v95, v148, v95
	v_cvt_pk_bf16_f32 v88, v92, v93
	v_cvt_pk_bf16_f32 v89, v94, v95
	ds_write_b64 v185, v[88:89] offset:4160
	v_sub_f32_e32 v137, v248, v137
	v_mul_f32_e32 v137, 0x3fb8aa3b, v137
	v_exp_f32_e32 v137, v137
	v_sub_f32_e32 v141, v249, v141
	v_mul_f32_e32 v141, 0x3fb8aa3b, v141
	v_exp_f32_e32 v141, v141
	v_sub_f32_e32 v145, v250, v145
	v_mul_f32_e32 v145, 0x3fb8aa3b, v145
	v_exp_f32_e32 v145, v145
	v_sub_f32_e32 v149, v251, v149
	v_mul_f32_e32 v149, 0x3fb8aa3b, v149
	v_exp_f32_e32 v149, v149
	s_waitcnt lgkmcnt(2)
	v_lshlrev_b32_e32 v92, 16, v242
	v_and_b32_e32 v93, 0xffff0000, v242
	v_lshlrev_b32_e32 v94, 16, v243
	v_and_b32_e32 v95, 0xffff0000, v243
	v_mul_f32_e32 v92, v137, v92
	v_mul_f32_e32 v93, v141, v93
	v_mul_f32_e32 v94, v145, v94
	v_mul_f32_e32 v95, v149, v95
	v_cvt_pk_bf16_f32 v90, v92, v93
	v_cvt_pk_bf16_f32 v91, v94, v95
	ds_write_b64 v185, v[90:91] offset:5200
	v_sub_f32_e32 v138, v248, v138
	v_mul_f32_e32 v138, 0x3fb8aa3b, v138
	v_exp_f32_e32 v138, v138
	v_sub_f32_e32 v142, v249, v142
	v_mul_f32_e32 v142, 0x3fb8aa3b, v142
	v_exp_f32_e32 v142, v142
	v_sub_f32_e32 v146, v250, v146
	v_mul_f32_e32 v146, 0x3fb8aa3b, v146
	v_exp_f32_e32 v146, v146
	v_sub_f32_e32 v150, v251, v150
	v_mul_f32_e32 v150, 0x3fb8aa3b, v150
	v_exp_f32_e32 v150, v150
	s_waitcnt lgkmcnt(1)
	v_lshlrev_b32_e32 v92, 16, v244
	v_and_b32_e32 v93, 0xffff0000, v244
	v_lshlrev_b32_e32 v94, 16, v245
	v_and_b32_e32 v95, 0xffff0000, v245
	v_mul_f32_e32 v92, v138, v92
	v_mul_f32_e32 v93, v142, v93
	v_mul_f32_e32 v94, v146, v94
	v_mul_f32_e32 v95, v150, v95
	v_cvt_pk_bf16_f32 v88, v92, v93
	v_cvt_pk_bf16_f32 v89, v94, v95
	ds_write_b64 v185, v[88:89] offset:6240
	v_sub_f32_e32 v139, v248, v139
	v_mul_f32_e32 v139, 0x3fb8aa3b, v139
	v_exp_f32_e32 v139, v139
	v_sub_f32_e32 v143, v249, v143
	v_mul_f32_e32 v143, 0x3fb8aa3b, v143
	v_exp_f32_e32 v143, v143
	v_sub_f32_e32 v147, v250, v147
	v_mul_f32_e32 v147, 0x3fb8aa3b, v147
	v_exp_f32_e32 v147, v147
	v_sub_f32_e32 v151, v251, v151
	v_mul_f32_e32 v151, 0x3fb8aa3b, v151
	v_exp_f32_e32 v151, v151
	s_waitcnt lgkmcnt(0)
	v_lshlrev_b32_e32 v92, 16, v246
	v_and_b32_e32 v93, 0xffff0000, v246
	v_lshlrev_b32_e32 v94, 16, v247
	v_and_b32_e32 v95, 0xffff0000, v247
	v_mul_f32_e32 v92, v139, v92
	v_mul_f32_e32 v93, v143, v93
	v_mul_f32_e32 v94, v147, v94
	v_mul_f32_e32 v95, v151, v95
	v_cvt_pk_bf16_f32 v90, v92, v93
	v_cvt_pk_bf16_f32 v91, v94, v95
	ds_write_b64 v185, v[90:91] offset:7280
	ds_read_b64 v[232:233], v185 offset:8320
	ds_read_b64 v[234:235], v185 offset:9360
	ds_read_b64 v[236:237], v185 offset:10400
	ds_read_b64 v[238:239], v185 offset:11440
	ds_read_b64 v[240:241], v185 offset:12480
	ds_read_b64 v[242:243], v185 offset:13520
	ds_read_b64 v[244:245], v185 offset:14560
	ds_read_b64 v[246:247], v185 offset:15600
	v_sub_f32_e32 v152, v248, v152
	v_mul_f32_e32 v152, 0x3fb8aa3b, v152
	v_exp_f32_e32 v152, v152
	v_sub_f32_e32 v156, v249, v156
	v_mul_f32_e32 v156, 0x3fb8aa3b, v156
	v_exp_f32_e32 v156, v156
	v_sub_f32_e32 v160, v250, v160
	v_mul_f32_e32 v160, 0x3fb8aa3b, v160
	v_exp_f32_e32 v160, v160
	v_sub_f32_e32 v164, v251, v164
	v_mul_f32_e32 v164, 0x3fb8aa3b, v164
	v_exp_f32_e32 v164, v164
	s_waitcnt lgkmcnt(7)
	v_lshlrev_b32_e32 v92, 16, v232
	v_and_b32_e32 v93, 0xffff0000, v232
	v_lshlrev_b32_e32 v94, 16, v233
	v_and_b32_e32 v95, 0xffff0000, v233
	v_mul_f32_e32 v92, v152, v92
	v_mul_f32_e32 v93, v156, v93
	v_mul_f32_e32 v94, v160, v94
	v_mul_f32_e32 v95, v164, v95
	v_cvt_pk_bf16_f32 v88, v92, v93
	v_cvt_pk_bf16_f32 v89, v94, v95
	ds_write_b64 v185, v[88:89] offset:8320
	v_sub_f32_e32 v153, v248, v153
	v_mul_f32_e32 v153, 0x3fb8aa3b, v153
	v_exp_f32_e32 v153, v153
	v_sub_f32_e32 v157, v249, v157
	v_mul_f32_e32 v157, 0x3fb8aa3b, v157
	v_exp_f32_e32 v157, v157
	v_sub_f32_e32 v161, v250, v161
	v_mul_f32_e32 v161, 0x3fb8aa3b, v161
	v_exp_f32_e32 v161, v161
	v_sub_f32_e32 v165, v251, v165
	v_mul_f32_e32 v165, 0x3fb8aa3b, v165
	v_exp_f32_e32 v165, v165
	s_waitcnt lgkmcnt(6)
	v_lshlrev_b32_e32 v92, 16, v234
	v_and_b32_e32 v93, 0xffff0000, v234
	v_lshlrev_b32_e32 v94, 16, v235
	v_and_b32_e32 v95, 0xffff0000, v235
	v_mul_f32_e32 v92, v153, v92
	v_mul_f32_e32 v93, v157, v93
	v_mul_f32_e32 v94, v161, v94
	v_mul_f32_e32 v95, v165, v95
	v_cvt_pk_bf16_f32 v90, v92, v93
	v_cvt_pk_bf16_f32 v91, v94, v95
	ds_write_b64 v185, v[90:91] offset:9360
	v_sub_f32_e32 v154, v248, v154
	v_mul_f32_e32 v154, 0x3fb8aa3b, v154
	v_exp_f32_e32 v154, v154
	v_sub_f32_e32 v158, v249, v158
	v_mul_f32_e32 v158, 0x3fb8aa3b, v158
	v_exp_f32_e32 v158, v158
	v_sub_f32_e32 v162, v250, v162
	v_mul_f32_e32 v162, 0x3fb8aa3b, v162
	v_exp_f32_e32 v162, v162
	v_sub_f32_e32 v166, v251, v166
	v_mul_f32_e32 v166, 0x3fb8aa3b, v166
	v_exp_f32_e32 v166, v166
	s_waitcnt lgkmcnt(5)
; __device__ __forceinline__ unsigned f2bf(float f) { unsigned u = __builtin_bit_cast(unsigned, f); return (u + 0x7fffu + ((u >> 16) & 1u)) >> 16; }
; __device__ __forceinline__ void phase_gla_kdec(Frame& F) {
;     ...
;             for (int s = 0; s < CH; ++s) { const float kv = bf2f(kt[s * KP + j]);
;                 kt[s * KP + j] = (bf16_t)f2bf(kv * __builtin_amdgcn_exp2f(1.4426950408889634f * (run - gc[s]))); }
;             DEC[(size_t)unit * QKW + j] = __builtin_amdgcn_exp2f(1.4426950408889634f * run); }
	v_lshlrev_b32_e32 v92, 16, v236
	v_and_b32_e32 v93, 0xffff0000, v236
	v_lshlrev_b32_e32 v94, 16, v237
	v_and_b32_e32 v95, 0xffff0000, v237
	v_mul_f32_e32 v92, v154, v92
	v_mul_f32_e32 v93, v158, v93
	v_mul_f32_e32 v94, v162, v94
	v_mul_f32_e32 v95, v166, v95
	v_cvt_pk_bf16_f32 v88, v92, v93
	v_cvt_pk_bf16_f32 v89, v94, v95
	ds_write_b64 v185, v[88:89] offset:10400
	v_sub_f32_e32 v155, v248, v155
	v_mul_f32_e32 v155, 0x3fb8aa3b, v155
	v_exp_f32_e32 v155, v155
	v_sub_f32_e32 v159, v249, v159
	v_mul_f32_e32 v159, 0x3fb8aa3b, v159
	v_exp_f32_e32 v159, v159
	v_sub_f32_e32 v163, v250, v163
	v_mul_f32_e32 v163, 0x3fb8aa3b, v163
	v_exp_f32_e32 v163, v163
	v_sub_f32_e32 v167, v251, v167
	v_mul_f32_e32 v167, 0x3fb8aa3b, v167
	v_exp_f32_e32 v167, v167
	s_waitcnt lgkmcnt(4)
	v_lshlrev_b32_e32 v92, 16, v238
	v_and_b32_e32 v93, 0xffff0000, v238
	v_lshlrev_b32_e32 v94, 16, v239
	v_and_b32_e32 v95, 0xffff0000, v239
	v_mul_f32_e32 v92, v155, v92
	v_mul_f32_e32 v93, v159, v93
	v_mul_f32_e32 v94, v163, v94
	v_mul_f32_e32 v95, v167, v95
	v_cvt_pk_bf16_f32 v90, v92, v93
	v_cvt_pk_bf16_f32 v91, v94, v95
	ds_write_b64 v185, v[90:91] offset:11440
	v_sub_f32_e32 v168, v248, v168
	v_mul_f32_e32 v168, 0x3fb8aa3b, v168
	v_exp_f32_e32 v168, v168
	v_sub_f32_e32 v172, v249, v172
	v_mul_f32_e32 v172, 0x3fb8aa3b, v172
	v_exp_f32_e32 v172, v172
	v_sub_f32_e32 v176, v250, v176
	v_mul_f32_e32 v176, 0x3fb8aa3b, v176
	v_exp_f32_e32 v176, v176
	v_sub_f32_e32 v180, v251, v180
	v_mul_f32_e32 v180, 0x3fb8aa3b, v180
	v_exp_f32_e32 v180, v180
	s_waitcnt lgkmcnt(3)
	v_lshlrev_b32_e32 v92, 16, v240
	v_and_b32_e32 v93, 0xffff0000, v240
	v_lshlrev_b32_e32 v94, 16, v241
	v_and_b32_e32 v95, 0xffff0000, v241
	v_mul_f32_e32 v92, v168, v92
	v_mul_f32_e32 v93, v172, v93
	v_mul_f32_e32 v94, v176, v94
	v_mul_f32_e32 v95, v180, v95
	v_cvt_pk_bf16_f32 v88, v92, v93
	v_cvt_pk_bf16_f32 v89, v94, v95
	ds_write_b64 v185, v[88:89] offset:12480
	v_sub_f32_e32 v169, v248, v169
	v_mul_f32_e32 v169, 0x3fb8aa3b, v169
	v_exp_f32_e32 v169, v169
	v_sub_f32_e32 v173, v249, v173
	v_mul_f32_e32 v173, 0x3fb8aa3b, v173
	v_exp_f32_e32 v173, v173
	v_sub_f32_e32 v177, v250, v177
	v_mul_f32_e32 v177, 0x3fb8aa3b, v177
	v_exp_f32_e32 v177, v177
	v_sub_f32_e32 v181, v251, v181
	v_mul_f32_e32 v181, 0x3fb8aa3b, v181
	v_exp_f32_e32 v181, v181
	s_waitcnt lgkmcnt(2)
	v_lshlrev_b32_e32 v92, 16, v242
	v_and_b32_e32 v93, 0xffff0000, v242
	v_lshlrev_b32_e32 v94, 16, v243
	v_and_b32_e32 v95, 0xffff0000, v243
	v_mul_f32_e32 v92, v169, v92
	v_mul_f32_e32 v93, v173, v93
	v_mul_f32_e32 v94, v177, v94
	v_mul_f32_e32 v95, v181, v95
	v_cvt_pk_bf16_f32 v90, v92, v93
	v_cvt_pk_bf16_f32 v91, v94, v95
	ds_write_b64 v185, v[90:91] offset:13520
	v_sub_f32_e32 v170, v248, v170
	v_mul_f32_e32 v170, 0x3fb8aa3b, v170
	v_exp_f32_e32 v170, v170
	v_sub_f32_e32 v174, v249, v174
	v_mul_f32_e32 v174, 0x3fb8aa3b, v174
	v_exp_f32_e32 v174, v174
	v_sub_f32_e32 v178, v250, v178
	v_mul_f32_e32 v178, 0x3fb8aa3b, v178
	v_exp_f32_e32 v178, v178
	v_sub_f32_e32 v182, v251, v182
	v_mul_f32_e32 v182, 0x3fb8aa3b, v182
	v_exp_f32_e32 v182, v182
	s_waitcnt lgkmcnt(1)
	v_lshlrev_b32_e32 v92, 16, v244
	v_and_b32_e32 v93, 0xffff0000, v244
	v_lshlrev_b32_e32 v94, 16, v245
	v_and_b32_e32 v95, 0xffff0000, v245
	v_mul_f32_e32 v92, v170, v92
	v_mul_f32_e32 v93, v174, v93
	v_mul_f32_e32 v94, v178, v94
	v_mul_f32_e32 v95, v182, v95
	v_cvt_pk_bf16_f32 v88, v92, v93
	v_cvt_pk_bf16_f32 v89, v94, v95
	ds_write_b64 v185, v[88:89] offset:14560
	v_sub_f32_e32 v171, v248, v171
	v_mul_f32_e32 v171, 0x3fb8aa3b, v171
	v_exp_f32_e32 v171, v171
	v_sub_f32_e32 v175, v249, v175
	v_mul_f32_e32 v175, 0x3fb8aa3b, v175
	v_exp_f32_e32 v175, v175
	v_sub_f32_e32 v179, v250, v179
	v_mul_f32_e32 v179, 0x3fb8aa3b, v179
	v_exp_f32_e32 v179, v179
	v_sub_f32_e32 v183, v251, v183
	v_mul_f32_e32 v183, 0x3fb8aa3b, v183
	v_exp_f32_e32 v183, v183
	s_waitcnt lgkmcnt(0)
	v_lshlrev_b32_e32 v92, 16, v246
	v_and_b32_e32 v93, 0xffff0000, v246
	v_lshlrev_b32_e32 v94, 16, v247
	v_and_b32_e32 v95, 0xffff0000, v247
	v_mul_f32_e32 v92, v171, v92
	v_mul_f32_e32 v93, v175, v93
	v_mul_f32_e32 v94, v179, v94
	v_mul_f32_e32 v95, v183, v95
	v_cvt_pk_bf16_f32 v90, v92, v93
	v_cvt_pk_bf16_f32 v91, v94, v95
	ds_write_b64 v185, v[90:91] offset:15600
	v_mov_b64_e32 v[92:93], v[82:83]
	v_mov_b64_e32 v[88:89], v[86:87]
	v_mov_b64_e32 v[90:91], v[84:85]
	v_mov_b64_e32 v[94:95], v[80:81]
	s_mov_b32 s0, 0
	s_branch .LBB0_819
